# gla_sample_item: low-rank gate weights / gate inputs / k,q loads issued together (global_load, one wait) instead of 17 serialized flat-load round trips
# speedup vs baseline: 1.0120x; 1.0058x over previous
; #define LAS __attribute__((address_space(3)))
; __device__ __forceinline__ float bf2f(unsigned b) { return __uint_as_float(b << 16); }
; __device__ __forceinline__ float softplus_(float x) { return fmaxf(x, 0.f) + __logf(1.f + __expf(-fabsf(x))); }
; __device__ __forceinline__ int opaque_tid() { int t = threadIdx.x; asm volatile("" : "+v"(t)); return t; }
; __device__ __forceinline__ void gla_sample_item(const Ctx& P, int l, int s, int h, LAS unsigned char* lds) {
;     const int tid = opaque_tid(), lane = tid & 63, w = __builtin_amdgcn_readfirstlane(tid >> 6);
;     LAS float* AL = (LAS float*)lds; LAS float* KK = AL + 128; LAS float* QQ = KK + 128; LAS float* OP = QQ + 128; LAS float* RED = OP + 8 * 256;
;     const bf16_t* Z = (const bf16_t*)(P.ws + WS_Z); bf16_t* OG = (bf16_t*)(P.ws + WS_OG);
;     const size_t row = (size_t)(MP + s);
;     const float* p_wg = INP(P, 16); const float* p_bg = INP(P, 17); const float* p_s0 = INP(P, 4); const float* p_gn = INP(P, 18);
;     if (tid < 128) { const int col = h * 128 + tid; float zg = p_bg[l * 512 + col];
; #pragma unroll
;         for (int r = 0; r < 16; ++r) zg += bf2f(Z[row * NZ + ZC_GLR + r]) * p_wg[((size_t)l * 16 + r) * 512 + col];
;         AL[tid] = __expf(-softplus_(-zg) * (1.f / 16.f)); KK[tid] = bf2f(Z[row * NZ + ZC_K + col]); QQ[tid] = bf2f(Z[row * NZ + ZC_Q + col]) * 0.08838834764831845f; }
.LBB0_454:
	s_cmpk_gt_i32 s63, 0x20f
	s_mov_b64 s[0:1], -1
	s_cbranch_scc0 .LBB0_468
	s_cmpk_gt_u32 s63, 0x21f
	s_cbranch_scc0 .LBB0_465
	s_add_i32 s12, s63, 0xfffffde0
	s_lshr_b32 s0, s12, 2
	s_or_b32 s30, s0, 0x4080
	v_readlane_b32 s0, v250, 14
	v_mov_b32_e32 v72, v188
	s_waitcnt lgkmcnt(0)
	v_mov_b32_e32 v0, s0
	s_barrier
	ds_read_b128 v[2:5], v0
	v_readlane_b32 s4, v250, 18
	v_readfirstlane_b32 s70, v72
	s_mul_hi_u32 s5, s30, 0x3a00
	v_mov_b32_e32 v0, s4
	s_waitcnt lgkmcnt(0)
	v_readfirstlane_b32 s15, v3
	v_readfirstlane_b32 s22, v2
	ds_read_b64 v[2:3], v0
	v_readlane_b32 s4, v250, 19
	v_readfirstlane_b32 s1, v5
	v_readfirstlane_b32 s0, v4
	v_mov_b32_e32 v0, s4
	s_waitcnt lgkmcnt(0)
	v_readfirstlane_b32 s13, v3
	v_readfirstlane_b32 s14, v2
	ds_read_b64 v[2:3], v0
	s_movk_i32 s4, 0x7f
	v_cmp_lt_i32_e32 vcc, s4, v72
	s_mul_i32 s4, s30, 0x3a00
	s_waitcnt lgkmcnt(0)
	v_readfirstlane_b32 s60, v3
	v_readfirstlane_b32 s61, v2
	s_and_saveexec_b64 s[8:9], vcc
	s_xor_b64 s[8:9], exec, s[8:9]
	s_or_saveexec_b64 s[8:9], s[8:9]
	s_and_b32 s68, s63, 3
	v_mov_b64_e32 v[2:3], s[4:5]
	v_lshl_add_u32 v73, v72, 2, 0
	s_xor_b64 exec, exec, s[8:9]
	s_cbranch_execz .LBB0_458
	v_lshl_add_u32 v2, s68, 7, v72
	v_readlane_b32 s10, v250, 52
	v_ashrrev_i32_e32 v3, 31, v2
	s_nop 0
	v_add_u32_e32 v4, s10, v2
	v_ashrrev_i32_e32 v5, 31, v4
	s_add_u32 s10, s16, s4
	v_lshl_add_u64 v[4:5], v[4:5], 2, s[0:1]
	s_addc_u32 s11, s17, s5
	v_readlane_b32 s0, v250, 53
	v_readlane_b32 s1, v250, 54
	s_add_u32 s0, s22, s0
	s_addc_u32 s1, s15, s1
	global_load_dword v0, v[4:5], off
	v_lshl_add_u64 v[4:5], v[2:3], 2, s[0:1]
	global_load_dwordx4 v[6:9], v192, s[10:11] offset:2048
	global_load_dwordx4 v[36:39], v192, s[10:11] offset:2064
	v_lshl_add_u64 v[2:3], v[2:3], 1, s[10:11]
	global_load_dword v14, v[4:5], off
	global_load_dword v15, v[4:5], off offset:2048
	v_mov_b32_e32 v10, v4
	v_mov_b32_e32 v11, v5
	v_add_co_u32_e32 v10, vcc, 0x1000, v10
	s_nop 1
	v_addc_co_u32_e32 v11, vcc, 0, v11, vcc
	global_load_dword v16, v[10:11], off
	global_load_dword v17, v[10:11], off offset:2048
	v_add_co_u32_e32 v10, vcc, 0x1000, v10
	s_nop 1
	v_addc_co_u32_e32 v11, vcc, 0, v11, vcc
	global_load_dword v18, v[10:11], off
	global_load_dword v19, v[10:11], off offset:2048
	v_add_co_u32_e32 v10, vcc, 0x1000, v10
	s_nop 1
	v_addc_co_u32_e32 v11, vcc, 0, v11, vcc
	global_load_dword v20, v[10:11], off
	global_load_dword v21, v[10:11], off offset:2048
	v_add_co_u32_e32 v10, vcc, 0x1000, v10
	s_nop 1
	v_addc_co_u32_e32 v11, vcc, 0, v11, vcc
	global_load_dword v22, v[10:11], off
	global_load_dword v23, v[10:11], off offset:2048
	v_add_co_u32_e32 v10, vcc, 0x1000, v10
	s_nop 1
	v_addc_co_u32_e32 v11, vcc, 0, v11, vcc
	global_load_dword v24, v[10:11], off
	global_load_dword v25, v[10:11], off offset:2048
	v_add_co_u32_e32 v10, vcc, 0x1000, v10
	s_nop 1
	v_addc_co_u32_e32 v11, vcc, 0, v11, vcc
	global_load_dword v26, v[10:11], off
	global_load_dword v27, v[10:11], off offset:2048
	v_add_co_u32_e32 v10, vcc, 0x1000, v10
	s_nop 1
	v_addc_co_u32_e32 v11, vcc, 0, v11, vcc
	global_load_dword v28, v[10:11], off
	global_load_dword v29, v[10:11], off offset:2048
	v_add_co_u32_e32 v2, vcc, 0x1000, v2
	s_nop 1
	v_addc_co_u32_e32 v3, vcc, 0, v3, vcc
	global_load_ushort v40, v[2:3], off offset:1024
	global_load_ushort v41, v[2:3], off
	s_waitcnt vmcnt(0)
	v_lshlrev_b32_e32 v10, 16, v6
	v_fmac_f32_e32 v0, v14, v10
	v_and_b32_e32 v10, 0xffff0000, v6
	v_fmac_f32_e32 v0, v15, v10
	v_lshlrev_b32_e32 v10, 16, v7
	v_fmac_f32_e32 v0, v16, v10
	v_and_b32_e32 v10, 0xffff0000, v7
	v_fmac_f32_e32 v0, v17, v10
	v_lshlrev_b32_e32 v10, 16, v8
	v_fmac_f32_e32 v0, v18, v10
	v_and_b32_e32 v10, 0xffff0000, v8
	v_fmac_f32_e32 v0, v19, v10
	v_lshlrev_b32_e32 v10, 16, v9
	v_fmac_f32_e32 v0, v20, v10
	v_and_b32_e32 v10, 0xffff0000, v9
	v_fmac_f32_e32 v0, v21, v10
	v_lshlrev_b32_e32 v10, 16, v36
	v_fmac_f32_e32 v0, v22, v10
	v_and_b32_e32 v10, 0xffff0000, v36
	v_fmac_f32_e32 v0, v23, v10
	v_lshlrev_b32_e32 v10, 16, v37
	v_fmac_f32_e32 v0, v24, v10
	v_and_b32_e32 v10, 0xffff0000, v37
	v_fmac_f32_e32 v0, v25, v10
	v_lshlrev_b32_e32 v10, 16, v38
	v_fmac_f32_e32 v0, v26, v10
	v_and_b32_e32 v10, 0xffff0000, v38
	v_fmac_f32_e32 v0, v27, v10
	v_lshlrev_b32_e32 v10, 16, v39
	v_fmac_f32_e32 v0, v28, v10
	v_and_b32_e32 v10, 0xffff0000, v39
	v_fmac_f32_e32 v0, v29, v10
	s_mov_b32 s0, 0xbfb8aa3b
	v_max_f32_e64 v4, -v0, 0
	v_mul_f32_e64 v0, |v0|, s0
	v_exp_f32_e32 v0, v0
	s_mov_b32 s0, 0x3f317217
	v_add_f32_e32 v0, 1.0, v0
	v_cmp_gt_f32_e32 vcc, s66, v0
	s_nop 1
	v_cndmask_b32_e64 v5, 0, 32, vcc
	v_ldexp_f32 v0, v0, v5
	v_log_f32_e32 v0, v0
	s_nop 0
	v_mul_f32_e32 v5, 0x3f317217, v0
	v_fma_f32 v5, v0, s0, -v5
	v_fmac_f32_e32 v5, 0x3377d1cf, v0
	s_mov_b32 s0, 0x7f800000
	v_fmac_f32_e32 v5, 0x3f317217, v0
	v_cmp_lt_f32_e64 s[0:1], |v0|, s0
	s_nop 1
	v_cndmask_b32_e64 v0, v0, v5, s[0:1]
	v_cndmask_b32_e32 v5, 0, v195, vcc
	v_sub_f32_e32 v0, v0, v5
	v_add_f32_e32 v0, v4, v0
	v_mul_f32_e32 v0, 0xbd800000, v0
	v_mul_f32_e32 v0, 0x3fb8aa3b, v0
	v_exp_f32_e32 v0, v0
	v_lshlrev_b32_e32 v4, 16, v40
	ds_write2st64_b32 v73, v0, v4 offset1:2
	v_lshlrev_b32_e32 v0, 16, v41
	v_mov_b64_e32 v[2:3], s[4:5]
	v_mul_f32_e32 v0, 0x3db504f3, v0
	ds_write_b32 v73, v0 offset:1024
